# branch-A/branch-B GEMM epilogues (in-place multiply / merge): gate and merge tile loads batched (16 loads in flight, one wait) instead of eight serialized load-wait-store groups
# speedup vs baseline: 1.0052x; 1.0052x over previous
; __device__ __forceinline__ float bf_lo(unsigned w) { return __uint_as_float(w << 16); }
; __device__ __forceinline__ float bf_hi(unsigned w) { return __uint_as_float(w & 0xffff0000u); }
; __device__ __forceinline__ u32x4 pack8(f32x4 a, f32x4 b) { u32x4 w; w.x = cvt_pk_bf16(a[0], a[1]); w.y = cvt_pk_bf16(a[2], a[3]); w.z = cvt_pk_bf16(b[0], b[1]); w.w = cvt_pk_bf16(b[2], b[3]); return w; }
;     __device__ __forceinline__ void operator()(const f32x4 (&acc)[2][2][4][2], const Unit& u, int wr, int wc, int fr, int fq) const {
;         const int row0 = u.pm * BM + wr * 64 + fr, c0 = u.pn * BM + wc * 32 + 8 * fq;
; #pragma unroll
;         for (int ai = 0; ai < 2; ++ai)
; #pragma unroll
;             for (int m = 0; m < 4; ++m) { bf16_t* rowp = T + (size_t)(row0 + ai * HALF + m * 16) * 2048 + c0;
; #pragma unroll
;                 for (int bj = 0; bj < 2; ++bj) { const u32x4 g = *(const u32x4*)(rowp + bj * HALF); const f32x4 v0 = acc[ai][bj][m][0], v1 = acc[ai][bj][m][1];
;                     const f32x4 o0 = {bf_lo(g.x) * v0[0], bf_hi(g.x) * v0[1], bf_lo(g.y) * v0[2], bf_hi(g.y) * v0[3]};
;                     const f32x4 o1 = {bf_lo(g.z) * v1[0], bf_hi(g.z) * v1[1], bf_lo(g.w) * v1[2], bf_hi(g.w) * v1[3]};
;                     *(u32x4*)(rowp + bj * HALF) = pack8(o0, o1); } }
.LBB0_681:
	s_andn2_b64 vcc, exec, s[2:3]
	s_mov_b64 s[2:3], -1
	v_lshlrev_b32_e32 v148, 12, v152
	v_lshl_add_u32 v148, v154, 1, v148
	s_lshl_b32 s98, s30, 20
	s_lshl_b32 s99, s59, 9
	s_add_u32 s98, s98, s99
	s_add_u32 s98, s10, s98
	s_addc_u32 s99, s11, 0
	global_load_dwordx4 v[160:163], v148, s[98:99]
	global_load_dwordx4 v[164:167], v148, s[98:99] offset:256
	s_add_u32 s98, s98, 0x10000
	s_addc_u32 s99, s99, 0
	global_load_dwordx4 v[168:171], v148, s[98:99]
	global_load_dwordx4 v[172:175], v148, s[98:99] offset:256
	s_add_u32 s98, s98, 0x10000
	s_addc_u32 s99, s99, 0
	global_load_dwordx4 v[176:179], v148, s[98:99]
	global_load_dwordx4 v[180:183], v148, s[98:99] offset:256
	s_add_u32 s98, s98, 0x10000
	s_addc_u32 s99, s99, 0
	global_load_dwordx4 v[184:187], v148, s[98:99]
	global_load_dwordx4 v[188:191], v148, s[98:99] offset:256
	s_add_u32 s98, s98, 0x50000
	s_addc_u32 s99, s99, 0
	global_load_dwordx4 v[192:195], v148, s[98:99]
	global_load_dwordx4 v[196:199], v148, s[98:99] offset:256
	s_add_u32 s98, s98, 0x10000
	s_addc_u32 s99, s99, 0
	global_load_dwordx4 v[200:203], v148, s[98:99]
	global_load_dwordx4 v[204:207], v148, s[98:99] offset:256
	s_add_u32 s98, s98, 0x10000
	s_addc_u32 s99, s99, 0
	global_load_dwordx4 v[208:211], v148, s[98:99]
	global_load_dwordx4 v[212:215], v148, s[98:99] offset:256
	s_add_u32 s98, s98, 0x10000
	s_addc_u32 s99, s99, 0
	global_load_dwordx4 v[216:219], v148, s[98:99]
	global_load_dwordx4 v[220:223], v148, s[98:99] offset:256
	s_waitcnt vmcnt(0)
	v_lshlrev_b32_e32 v224, 16, v160
	v_and_b32_e32 v225, 0xffff0000, v160
	v_mul_f32_e32 v224, v224, v124
	v_mul_f32_e32 v225, v225, v125
	v_cvt_pk_bf16_f32 v160, v224, v225
	v_lshlrev_b32_e32 v228, 16, v161
	v_and_b32_e32 v229, 0xffff0000, v161
	v_mul_f32_e32 v228, v228, v126
	v_mul_f32_e32 v229, v229, v127
	v_cvt_pk_bf16_f32 v161, v228, v229
	v_lshlrev_b32_e32 v224, 16, v162
	v_and_b32_e32 v225, 0xffff0000, v162
	v_mul_f32_e32 v224, v224, v120
	v_mul_f32_e32 v225, v225, v121
	v_cvt_pk_bf16_f32 v162, v224, v225
	v_lshlrev_b32_e32 v228, 16, v163
	v_and_b32_e32 v229, 0xffff0000, v163
	v_mul_f32_e32 v228, v228, v122
	v_mul_f32_e32 v229, v229, v123
	v_cvt_pk_bf16_f32 v163, v228, v229
	v_lshlrev_b32_e32 v224, 16, v164
	v_and_b32_e32 v225, 0xffff0000, v164
	v_mul_f32_e32 v224, v224, v112
	v_mul_f32_e32 v225, v225, v113
	v_cvt_pk_bf16_f32 v164, v224, v225
	v_lshlrev_b32_e32 v228, 16, v165
	v_and_b32_e32 v229, 0xffff0000, v165
	v_mul_f32_e32 v228, v228, v114
	v_mul_f32_e32 v229, v229, v115
	v_cvt_pk_bf16_f32 v165, v228, v229
	v_lshlrev_b32_e32 v224, 16, v166
	v_and_b32_e32 v225, 0xffff0000, v166
	v_mul_f32_e32 v224, v224, v104
	v_mul_f32_e32 v225, v225, v105
	v_cvt_pk_bf16_f32 v166, v224, v225
	v_lshlrev_b32_e32 v228, 16, v167
	v_and_b32_e32 v229, 0xffff0000, v167
	v_mul_f32_e32 v228, v228, v106
	v_mul_f32_e32 v229, v229, v107
	v_cvt_pk_bf16_f32 v167, v228, v229
	v_lshlrev_b32_e32 v224, 16, v168
	v_and_b32_e32 v225, 0xffff0000, v168
	v_mul_f32_e32 v224, v224, v116
	v_mul_f32_e32 v225, v225, v117
	v_cvt_pk_bf16_f32 v168, v224, v225
	v_lshlrev_b32_e32 v228, 16, v169
	v_and_b32_e32 v229, 0xffff0000, v169
	v_mul_f32_e32 v228, v228, v118
	v_mul_f32_e32 v229, v229, v119
	v_cvt_pk_bf16_f32 v169, v228, v229
	v_lshlrev_b32_e32 v224, 16, v170
	v_and_b32_e32 v225, 0xffff0000, v170
	v_mul_f32_e32 v224, v224, v108
	v_mul_f32_e32 v225, v225, v109
	v_cvt_pk_bf16_f32 v170, v224, v225
	v_lshlrev_b32_e32 v228, 16, v171
	v_and_b32_e32 v229, 0xffff0000, v171
	v_mul_f32_e32 v228, v228, v110
	v_mul_f32_e32 v229, v229, v111
	v_cvt_pk_bf16_f32 v171, v228, v229
	v_lshlrev_b32_e32 v224, 16, v172
	v_and_b32_e32 v225, 0xffff0000, v172
	v_mul_f32_e32 v224, v224, v100
	v_mul_f32_e32 v225, v225, v101
	v_cvt_pk_bf16_f32 v172, v224, v225
	v_lshlrev_b32_e32 v228, 16, v173
	v_and_b32_e32 v229, 0xffff0000, v173
	v_mul_f32_e32 v228, v228, v102
	v_mul_f32_e32 v229, v229, v103
	v_cvt_pk_bf16_f32 v173, v228, v229
	v_lshlrev_b32_e32 v224, 16, v174
	v_and_b32_e32 v225, 0xffff0000, v174
	v_mul_f32_e32 v224, v224, v96
	v_mul_f32_e32 v225, v225, v97
	v_cvt_pk_bf16_f32 v174, v224, v225
	v_lshlrev_b32_e32 v228, 16, v175
	v_and_b32_e32 v229, 0xffff0000, v175
	v_mul_f32_e32 v228, v228, v98
	v_mul_f32_e32 v229, v229, v99
	v_cvt_pk_bf16_f32 v175, v228, v229
	v_lshlrev_b32_e32 v224, 16, v176
	v_and_b32_e32 v225, 0xffff0000, v176
	v_mul_f32_e32 v224, v224, v92
	v_mul_f32_e32 v225, v225, v93
	v_cvt_pk_bf16_f32 v176, v224, v225
	v_lshlrev_b32_e32 v228, 16, v177
	v_and_b32_e32 v229, 0xffff0000, v177
	v_mul_f32_e32 v228, v228, v94
	v_mul_f32_e32 v229, v229, v95
	v_cvt_pk_bf16_f32 v177, v228, v229
	v_lshlrev_b32_e32 v224, 16, v178
	v_and_b32_e32 v225, 0xffff0000, v178
	v_mul_f32_e32 v224, v224, v88
	v_mul_f32_e32 v225, v225, v89
	v_cvt_pk_bf16_f32 v178, v224, v225
	v_lshlrev_b32_e32 v228, 16, v179
	v_and_b32_e32 v229, 0xffff0000, v179
	v_mul_f32_e32 v228, v228, v90
	v_mul_f32_e32 v229, v229, v91
	v_cvt_pk_bf16_f32 v179, v228, v229
	v_lshlrev_b32_e32 v224, 16, v180
	v_and_b32_e32 v225, 0xffff0000, v180
	v_mul_f32_e32 v224, v224, v84
	v_mul_f32_e32 v225, v225, v85
	v_cvt_pk_bf16_f32 v180, v224, v225
	v_lshlrev_b32_e32 v228, 16, v181
	v_and_b32_e32 v229, 0xffff0000, v181
	v_mul_f32_e32 v228, v228, v86
	v_mul_f32_e32 v229, v229, v87
	v_cvt_pk_bf16_f32 v181, v228, v229
	v_lshlrev_b32_e32 v224, 16, v182
	v_and_b32_e32 v225, 0xffff0000, v182
	v_mul_f32_e32 v224, v224, v80
	v_mul_f32_e32 v225, v225, v81
	v_cvt_pk_bf16_f32 v182, v224, v225
	v_lshlrev_b32_e32 v228, 16, v183
	v_and_b32_e32 v229, 0xffff0000, v183
	v_mul_f32_e32 v228, v228, v82
	v_mul_f32_e32 v229, v229, v83
	v_cvt_pk_bf16_f32 v183, v228, v229
	v_lshlrev_b32_e32 v224, 16, v184
; __device__ __forceinline__ float bf_lo(unsigned w) { return __uint_as_float(w << 16); }
; __device__ __forceinline__ float bf_hi(unsigned w) { return __uint_as_float(w & 0xffff0000u); }
; __device__ __forceinline__ u32x4 pack8(f32x4 a, f32x4 b) { u32x4 w; w.x = cvt_pk_bf16(a[0], a[1]); w.y = cvt_pk_bf16(a[2], a[3]); w.z = cvt_pk_bf16(b[0], b[1]); w.w = cvt_pk_bf16(b[2], b[3]); return w; }
;     __device__ __forceinline__ void operator()(const f32x4 (&acc)[2][2][4][2], const Unit& u, int wr, int wc, int fr, int fq) const {
;         const int row0 = u.pm * BM + wr * 64 + fr, c0 = u.pn * BM + wc * 32 + 8 * fq;
; #pragma unroll
;         for (int ai = 0; ai < 2; ++ai)
; #pragma unroll
;             for (int m = 0; m < 4; ++m) { bf16_t* rowp = T + (size_t)(row0 + ai * HALF + m * 16) * 2048 + c0;
; #pragma unroll
;                 for (int bj = 0; bj < 2; ++bj) { const u32x4 g = *(const u32x4*)(rowp + bj * HALF); const f32x4 v0 = acc[ai][bj][m][0], v1 = acc[ai][bj][m][1];
;                     const f32x4 o0 = {bf_lo(g.x) * v0[0], bf_hi(g.x) * v0[1], bf_lo(g.y) * v0[2], bf_hi(g.y) * v0[3]};
;                     const f32x4 o1 = {bf_lo(g.z) * v1[0], bf_hi(g.z) * v1[1], bf_lo(g.w) * v1[2], bf_hi(g.w) * v1[3]};
;                     *(u32x4*)(rowp + bj * HALF) = pack8(o0, o1); } }
	v_and_b32_e32 v225, 0xffff0000, v184
	v_mul_f32_e32 v224, v224, v76
	v_mul_f32_e32 v225, v225, v77
	v_cvt_pk_bf16_f32 v184, v224, v225
	v_lshlrev_b32_e32 v228, 16, v185
	v_and_b32_e32 v229, 0xffff0000, v185
	v_mul_f32_e32 v228, v228, v78
	v_mul_f32_e32 v229, v229, v79
	v_cvt_pk_bf16_f32 v185, v228, v229
	v_lshlrev_b32_e32 v224, 16, v186
	v_and_b32_e32 v225, 0xffff0000, v186
	v_mul_f32_e32 v224, v224, v72
	v_mul_f32_e32 v225, v225, v73
	v_cvt_pk_bf16_f32 v186, v224, v225
	v_lshlrev_b32_e32 v228, 16, v187
	v_and_b32_e32 v229, 0xffff0000, v187
	v_mul_f32_e32 v228, v228, v74
	v_mul_f32_e32 v229, v229, v75
	v_cvt_pk_bf16_f32 v187, v228, v229
	v_lshlrev_b32_e32 v224, 16, v188
	v_and_b32_e32 v225, 0xffff0000, v188
	v_mul_f32_e32 v224, v224, v68
	v_mul_f32_e32 v225, v225, v69
	v_cvt_pk_bf16_f32 v188, v224, v225
	v_lshlrev_b32_e32 v228, 16, v189
	v_and_b32_e32 v229, 0xffff0000, v189
	v_mul_f32_e32 v228, v228, v70
	v_mul_f32_e32 v229, v229, v71
	v_cvt_pk_bf16_f32 v189, v228, v229
	v_lshlrev_b32_e32 v224, 16, v190
	v_and_b32_e32 v225, 0xffff0000, v190
	v_mul_f32_e32 v224, v224, v64
	v_mul_f32_e32 v225, v225, v65
	v_cvt_pk_bf16_f32 v190, v224, v225
	v_lshlrev_b32_e32 v228, 16, v191
	v_and_b32_e32 v229, 0xffff0000, v191
	v_mul_f32_e32 v228, v228, v66
	v_mul_f32_e32 v229, v229, v67
	v_cvt_pk_bf16_f32 v191, v228, v229
	v_lshlrev_b32_e32 v224, 16, v192
	v_and_b32_e32 v225, 0xffff0000, v192
	v_mul_f32_e32 v224, v224, v60
	v_mul_f32_e32 v225, v225, v61
	v_cvt_pk_bf16_f32 v192, v224, v225
	v_lshlrev_b32_e32 v228, 16, v193
	v_and_b32_e32 v229, 0xffff0000, v193
	v_mul_f32_e32 v228, v228, v62
	v_mul_f32_e32 v229, v229, v63
	v_cvt_pk_bf16_f32 v193, v228, v229
	v_lshlrev_b32_e32 v224, 16, v194
	v_and_b32_e32 v225, 0xffff0000, v194
	v_mul_f32_e32 v224, v224, v56
	v_mul_f32_e32 v225, v225, v57
	v_cvt_pk_bf16_f32 v194, v224, v225
	v_lshlrev_b32_e32 v228, 16, v195
	v_and_b32_e32 v229, 0xffff0000, v195
	v_mul_f32_e32 v228, v228, v58
	v_mul_f32_e32 v229, v229, v59
	v_cvt_pk_bf16_f32 v195, v228, v229
	v_lshlrev_b32_e32 v224, 16, v196
	v_and_b32_e32 v225, 0xffff0000, v196
	v_mul_f32_e32 v224, v224, v52
	v_mul_f32_e32 v225, v225, v53
	v_cvt_pk_bf16_f32 v196, v224, v225
	v_lshlrev_b32_e32 v228, 16, v197
	v_and_b32_e32 v229, 0xffff0000, v197
	v_mul_f32_e32 v228, v228, v54
	v_mul_f32_e32 v229, v229, v55
	v_cvt_pk_bf16_f32 v197, v228, v229
	v_lshlrev_b32_e32 v224, 16, v198
	v_and_b32_e32 v225, 0xffff0000, v198
	v_mul_f32_e32 v224, v224, v48
	v_mul_f32_e32 v225, v225, v49
	v_cvt_pk_bf16_f32 v198, v224, v225
	v_lshlrev_b32_e32 v228, 16, v199
	v_and_b32_e32 v229, 0xffff0000, v199
	v_mul_f32_e32 v228, v228, v50
	v_mul_f32_e32 v229, v229, v51
	v_cvt_pk_bf16_f32 v199, v228, v229
	v_lshlrev_b32_e32 v224, 16, v200
	v_and_b32_e32 v225, 0xffff0000, v200
	v_mul_f32_e32 v224, v224, v44
	v_mul_f32_e32 v225, v225, v45
	v_cvt_pk_bf16_f32 v200, v224, v225
	v_lshlrev_b32_e32 v228, 16, v201
	v_and_b32_e32 v229, 0xffff0000, v201
	v_mul_f32_e32 v228, v228, v46
	v_mul_f32_e32 v229, v229, v47
	v_cvt_pk_bf16_f32 v201, v228, v229
	v_lshlrev_b32_e32 v224, 16, v202
	v_and_b32_e32 v225, 0xffff0000, v202
	v_mul_f32_e32 v224, v224, v40
	v_mul_f32_e32 v225, v225, v41
	v_cvt_pk_bf16_f32 v202, v224, v225
	v_lshlrev_b32_e32 v228, 16, v203
	v_and_b32_e32 v229, 0xffff0000, v203
	v_mul_f32_e32 v228, v228, v42
	v_mul_f32_e32 v229, v229, v43
	v_cvt_pk_bf16_f32 v203, v228, v229
	v_lshlrev_b32_e32 v224, 16, v204
	v_and_b32_e32 v225, 0xffff0000, v204
	v_mul_f32_e32 v224, v224, v32
	v_mul_f32_e32 v225, v225, v33
	v_cvt_pk_bf16_f32 v204, v224, v225
	v_lshlrev_b32_e32 v228, 16, v205
	v_and_b32_e32 v229, 0xffff0000, v205
	v_mul_f32_e32 v228, v228, v34
	v_mul_f32_e32 v229, v229, v35
	v_cvt_pk_bf16_f32 v205, v228, v229
	v_lshlrev_b32_e32 v224, 16, v206
	v_and_b32_e32 v225, 0xffff0000, v206
	v_mul_f32_e32 v224, v224, v24
	v_mul_f32_e32 v225, v225, v25
	v_cvt_pk_bf16_f32 v206, v224, v225
	v_lshlrev_b32_e32 v228, 16, v207
	v_and_b32_e32 v229, 0xffff0000, v207
	v_mul_f32_e32 v228, v228, v26
	v_mul_f32_e32 v229, v229, v27
	v_cvt_pk_bf16_f32 v207, v228, v229
	v_lshlrev_b32_e32 v224, 16, v208
; __device__ __forceinline__ float bf_lo(unsigned w) { return __uint_as_float(w << 16); }
; __device__ __forceinline__ float bf_hi(unsigned w) { return __uint_as_float(w & 0xffff0000u); }
; __device__ __forceinline__ u32x4 pack8(f32x4 a, f32x4 b) { u32x4 w; w.x = cvt_pk_bf16(a[0], a[1]); w.y = cvt_pk_bf16(a[2], a[3]); w.z = cvt_pk_bf16(b[0], b[1]); w.w = cvt_pk_bf16(b[2], b[3]); return w; }
;     __device__ __forceinline__ void operator()(const f32x4 (&acc)[2][2][4][2], const Unit& u, int wr, int wc, int fr, int fq) const {
;         const int row0 = u.pm * BM + wr * 64 + fr, c0 = u.pn * BM + wc * 32 + 8 * fq;
; #pragma unroll
;         for (int ai = 0; ai < 2; ++ai)
; #pragma unroll
;             for (int m = 0; m < 4; ++m) { bf16_t* rowp = T + (size_t)(row0 + ai * HALF + m * 16) * 2048 + c0;
; #pragma unroll
;                 for (int bj = 0; bj < 2; ++bj) { const u32x4 g = *(const u32x4*)(rowp + bj * HALF); const f32x4 v0 = acc[ai][bj][m][0], v1 = acc[ai][bj][m][1];
;                     const f32x4 o0 = {bf_lo(g.x) * v0[0], bf_hi(g.x) * v0[1], bf_lo(g.y) * v0[2], bf_hi(g.y) * v0[3]};
;                     const f32x4 o1 = {bf_lo(g.z) * v1[0], bf_hi(g.z) * v1[1], bf_lo(g.w) * v1[2], bf_hi(g.w) * v1[3]};
;                     *(u32x4*)(rowp + bj * HALF) = pack8(o0, o1); } }
	v_and_b32_e32 v225, 0xffff0000, v208
	v_mul_f32_e32 v224, v224, v36
	v_mul_f32_e32 v225, v225, v37
	v_cvt_pk_bf16_f32 v208, v224, v225
	v_lshlrev_b32_e32 v228, 16, v209
	v_and_b32_e32 v229, 0xffff0000, v209
	v_mul_f32_e32 v228, v228, v38
	v_mul_f32_e32 v229, v229, v39
	v_cvt_pk_bf16_f32 v209, v228, v229
	v_lshlrev_b32_e32 v224, 16, v210
	v_and_b32_e32 v225, 0xffff0000, v210
	v_mul_f32_e32 v224, v224, v28
	v_mul_f32_e32 v225, v225, v29
	v_cvt_pk_bf16_f32 v210, v224, v225
	v_lshlrev_b32_e32 v228, 16, v211
	v_and_b32_e32 v229, 0xffff0000, v211
	v_mul_f32_e32 v228, v228, v30
	v_mul_f32_e32 v229, v229, v31
	v_cvt_pk_bf16_f32 v211, v228, v229
	v_lshlrev_b32_e32 v224, 16, v212
	v_and_b32_e32 v225, 0xffff0000, v212
	v_mul_f32_e32 v224, v224, v16
	v_mul_f32_e32 v225, v225, v17
	v_cvt_pk_bf16_f32 v212, v224, v225
	v_lshlrev_b32_e32 v228, 16, v213
	v_and_b32_e32 v229, 0xffff0000, v213
	v_mul_f32_e32 v228, v228, v18
	v_mul_f32_e32 v229, v229, v19
	v_cvt_pk_bf16_f32 v213, v228, v229
	v_lshlrev_b32_e32 v224, 16, v214
	v_and_b32_e32 v225, 0xffff0000, v214
	v_mul_f32_e32 v224, v224, v8
	v_mul_f32_e32 v225, v225, v9
	v_cvt_pk_bf16_f32 v214, v224, v225
	v_lshlrev_b32_e32 v228, 16, v215
	v_and_b32_e32 v229, 0xffff0000, v215
	v_mul_f32_e32 v228, v228, v10
	v_mul_f32_e32 v229, v229, v11
	v_cvt_pk_bf16_f32 v215, v228, v229
	v_lshlrev_b32_e32 v224, 16, v216
	v_and_b32_e32 v225, 0xffff0000, v216
	v_mul_f32_e32 v224, v224, v20
	v_mul_f32_e32 v225, v225, v21
	v_cvt_pk_bf16_f32 v216, v224, v225
	v_lshlrev_b32_e32 v228, 16, v217
	v_and_b32_e32 v229, 0xffff0000, v217
	v_mul_f32_e32 v228, v228, v22
	v_mul_f32_e32 v229, v229, v23
	v_cvt_pk_bf16_f32 v217, v228, v229
	v_lshlrev_b32_e32 v224, 16, v218
	v_and_b32_e32 v225, 0xffff0000, v218
	v_mul_f32_e32 v224, v224, v12
	v_mul_f32_e32 v225, v225, v13
	v_cvt_pk_bf16_f32 v218, v224, v225
	v_lshlrev_b32_e32 v228, 16, v219
	v_and_b32_e32 v229, 0xffff0000, v219
	v_mul_f32_e32 v228, v228, v14
	v_mul_f32_e32 v229, v229, v15
	v_cvt_pk_bf16_f32 v219, v228, v229
	v_lshlrev_b32_e32 v224, 16, v220
	v_and_b32_e32 v225, 0xffff0000, v220
	v_mul_f32_e32 v224, v224, v4
	v_mul_f32_e32 v225, v225, v5
	v_cvt_pk_bf16_f32 v220, v224, v225
	v_lshlrev_b32_e32 v228, 16, v221
	v_and_b32_e32 v229, 0xffff0000, v221
	v_mul_f32_e32 v228, v228, v6
	v_mul_f32_e32 v229, v229, v7
	v_cvt_pk_bf16_f32 v221, v228, v229
	v_lshlrev_b32_e32 v224, 16, v222
	v_and_b32_e32 v225, 0xffff0000, v222
	v_mul_f32_e32 v224, v224, v0
	v_mul_f32_e32 v225, v225, v1
	v_cvt_pk_bf16_f32 v222, v224, v225
	v_lshlrev_b32_e32 v228, 16, v223
	v_and_b32_e32 v229, 0xffff0000, v223
	v_mul_f32_e32 v228, v228, v2
	v_mul_f32_e32 v229, v229, v3
	v_cvt_pk_bf16_f32 v223, v228, v229
	s_sub_u32 s98, s98, 0xb0000
	s_subb_u32 s99, s99, 0
	global_store_dwordx4 v148, v[160:163], s[98:99]
	global_store_dwordx4 v148, v[164:167], s[98:99] offset:256
	s_add_u32 s98, s98, 0x10000
	s_addc_u32 s99, s99, 0
	global_store_dwordx4 v148, v[168:171], s[98:99]
	global_store_dwordx4 v148, v[172:175], s[98:99] offset:256
	s_add_u32 s98, s98, 0x10000
	s_addc_u32 s99, s99, 0
	global_store_dwordx4 v148, v[176:179], s[98:99]
	global_store_dwordx4 v148, v[180:183], s[98:99] offset:256
	s_add_u32 s98, s98, 0x10000
	s_addc_u32 s99, s99, 0
	global_store_dwordx4 v148, v[184:187], s[98:99]
	global_store_dwordx4 v148, v[188:191], s[98:99] offset:256
	s_add_u32 s98, s98, 0x50000
	s_addc_u32 s99, s99, 0
	global_store_dwordx4 v148, v[192:195], s[98:99]
	global_store_dwordx4 v148, v[196:199], s[98:99] offset:256
	s_add_u32 s98, s98, 0x10000
	s_addc_u32 s99, s99, 0
	global_store_dwordx4 v148, v[200:203], s[98:99]
	global_store_dwordx4 v148, v[204:207], s[98:99] offset:256
	s_add_u32 s98, s98, 0x10000
	s_addc_u32 s99, s99, 0
	global_store_dwordx4 v148, v[208:211], s[98:99]
	global_store_dwordx4 v148, v[212:215], s[98:99] offset:256
	s_add_u32 s98, s98, 0x10000
	s_addc_u32 s99, s99, 0
	global_store_dwordx4 v148, v[216:219], s[98:99]
	global_store_dwordx4 v148, v[220:223], s[98:99] offset:256
	s_cbranch_vccnz .LBB0_670
	s_andn2_b64 vcc, exec, s[6:7]
	s_cbranch_vccnz .LBB0_669
	s_barrier
	s_branch .LBB0_669
